# ln1_router: dot16x2 rewritten with packed FMAs as in P0
# speedup vs baseline: 1.2356x; 1.0033x over previous
.LBB0_802:
	s_add_i32 s25, s18, s78
	s_cmp_lt_i32 s25, 0xc000
	s_cselect_b32 s16, s25, s18
	s_ashr_i32 s19, s18, 31
	s_lshl_b64 s[20:21], s[18:19], 11
	s_ashr_i32 s17, s16, 31
	s_waitcnt vmcnt(9)
	v_lshl_add_u64 v[40:41], v[36:37], 0, s[20:21]
	s_lshl_b64 s[22:23], s[16:17], 11
	global_load_dwordx2 v[42:43], v[40:41], off
	s_waitcnt lgkmcnt(0)
	global_load_dwordx2 v[44:45], v[40:41], off offset:512
	global_load_dwordx2 v[46:47], v[40:41], off offset:1024
	global_load_dwordx2 v[50:51], v[40:41], off offset:1536
	v_lshl_add_u64 v[40:41], v[36:37], 0, s[22:23]
	global_load_dwordx2 v[52:53], v[40:41], off
	global_load_dwordx2 v[54:55], v[40:41], off offset:512
	global_load_dwordx2 v[62:63], v[40:41], off offset:1024
	global_load_dwordx2 v[72:73], v[40:41], off offset:1536
	s_lshl_b64 s[26:27], s[18:19], 10
	s_lshl_b64 s[28:29], s[16:17], 10
	s_waitcnt vmcnt(7)
	v_lshlrev_b32_e32 v41, 16, v43
	v_lshlrev_b32_e32 v40, 16, v42
	v_and_b32_e32 v93, 0xffff0000, v43
	v_and_b32_e32 v92, 0xffff0000, v42
	s_waitcnt vmcnt(6)
	v_lshlrev_b32_e32 v49, 16, v45
	v_lshlrev_b32_e32 v48, 16, v44
	v_and_b32_e32 v95, 0xffff0000, v45
	v_and_b32_e32 v94, 0xffff0000, v44
	s_waitcnt vmcnt(5)
	v_lshlrev_b32_e32 v56, 16, v46
	v_and_b32_e32 v57, 0xffff0000, v46
	v_lshlrev_b32_e32 v58, 16, v47
	v_and_b32_e32 v59, 0xffff0000, v47
	v_pk_add_f32 v[42:43], v[40:41], v[92:93]
	s_waitcnt vmcnt(3)
	v_lshlrev_b32_e32 v45, 16, v53
	v_lshlrev_b32_e32 v44, 16, v52
	v_and_b32_e32 v97, 0xffff0000, v53
	v_and_b32_e32 v96, 0xffff0000, v52
	v_pk_add_f32 v[46:47], v[48:49], v[94:95]
	s_waitcnt vmcnt(2)
	v_lshlrev_b32_e32 v53, 16, v55
	v_lshlrev_b32_e32 v52, 16, v54
	v_and_b32_e32 v55, 0xffff0000, v55
	v_and_b32_e32 v54, 0xffff0000, v54
	v_lshlrev_b32_e32 v71, 16, v50
	v_and_b32_e32 v67, 0xffff0000, v50
	v_lshlrev_b32_e32 v69, 16, v51
	v_and_b32_e32 v65, 0xffff0000, v51
	v_add_f32_e32 v68, v56, v57
	v_add_f32_e32 v64, v58, v59
	v_add_f32_e32 v66, v42, v43
	v_pk_add_f32 v[42:43], v[44:45], v[96:97]
	v_pk_add_f32 v[50:51], v[52:53], v[54:55]
	v_pk_add_f32 v[46:47], v[46:47], v[46:47] op_sel:[0,1] op_sel_hi:[1,0]
	s_waitcnt vmcnt(1)
	v_lshlrev_b32_e32 v60, 16, v62
	v_and_b32_e32 v61, 0xffff0000, v62
	v_lshlrev_b32_e32 v80, 16, v63
	v_and_b32_e32 v81, 0xffff0000, v63
	s_waitcnt vmcnt(0)
	v_and_b32_e32 v75, 0xffff0000, v72
	v_pk_add_f32 v[62:63], v[68:69], v[64:65]
	v_add_f32_e32 v70, 0, v66
	v_add_f32_e32 v64, v42, v43
	v_mov_b32_e32 v47, v67
	v_pk_add_f32 v[42:43], v[50:51], v[50:51] op_sel:[0,1] op_sel_hi:[1,0]
	v_lshlrev_b32_e32 v79, 16, v72
	v_lshlrev_b32_e32 v77, 16, v73
	v_and_b32_e32 v73, 0xffff0000, v73
	v_add_f32_e32 v76, v60, v61
	v_add_f32_e32 v72, v80, v81
	v_add_f32_e32 v78, 0, v64
	v_pk_add_f32 v[46:47], v[70:71], v[46:47]
	v_mov_b32_e32 v43, v75
	v_pk_add_f32 v[50:51], v[76:77], v[72:73]
	v_pk_add_f32 v[46:47], v[46:47], v[62:63]
	v_pk_add_f32 v[42:43], v[78:79], v[42:43]
	v_add_f32_e32 v46, v46, v47
	v_pk_add_f32 v[42:43], v[42:43], v[50:51]
	ds_bpermute_b32 v47, v82, v46
	v_add_f32_e32 v42, v42, v43
	ds_bpermute_b32 v43, v82, v42
	s_waitcnt lgkmcnt(1)
	v_add_f32_e32 v46, v46, v47
	ds_bpermute_b32 v47, v83, v46
	s_waitcnt lgkmcnt(1)
	v_add_f32_e32 v42, v42, v43
	ds_bpermute_b32 v43, v83, v42
	s_waitcnt lgkmcnt(1)
	v_add_f32_e32 v46, v46, v47
	ds_bpermute_b32 v47, v84, v46
	s_waitcnt lgkmcnt(1)
	v_add_f32_e32 v42, v42, v43
	ds_bpermute_b32 v43, v84, v42
	s_waitcnt lgkmcnt(1)
	v_add_f32_e32 v46, v46, v47
	ds_bpermute_b32 v47, v85, v46
	s_waitcnt lgkmcnt(1)
	v_add_f32_e32 v42, v42, v43
	ds_bpermute_b32 v43, v85, v42
	s_waitcnt lgkmcnt(1)
	v_add_f32_e32 v46, v46, v47
	ds_bpermute_b32 v47, v86, v46
	s_waitcnt lgkmcnt(1)
	v_add_f32_e32 v42, v42, v43
	ds_bpermute_b32 v43, v86, v42
	s_waitcnt lgkmcnt(1)
	v_add_f32_e32 v46, v46, v47
	ds_bpermute_b32 v47, v87, v46
	s_waitcnt lgkmcnt(1)
	v_add_f32_e32 v42, v42, v43
	ds_bpermute_b32 v43, v87, v42
	s_waitcnt lgkmcnt(1)
	v_add_f32_e32 v64, v46, v47
	v_fmac_f32_e32 v92, 0xba800000, v64
	s_waitcnt lgkmcnt(0)
	v_add_f32_e32 v66, v42, v43
	v_fmac_f32_e32 v93, 0xba800000, v64
	v_fmac_f32_e32 v41, 0xba800000, v64
	v_fmac_f32_e32 v40, 0xba800000, v64
	v_fmac_f32_e32 v96, 0xba800000, v66
	v_fmac_f32_e32 v97, 0xba800000, v66
	v_fmac_f32_e32 v45, 0xba800000, v66
	v_mov_b32_e32 v42, v41
	v_mov_b32_e32 v43, v93
	v_mov_b32_e32 v41, v92
	v_fmac_f32_e32 v44, 0xba800000, v66
	v_pk_mul_f32 v[62:63], v[42:43], v[42:43]
	v_pk_mul_f32 v[92:93], v[40:41], v[40:41]
	v_mov_b32_e32 v46, v45
	v_mov_b32_e32 v47, v97
	v_mov_b32_e32 v45, v96
	v_fmac_f32_e32 v94, 0xba800000, v64
	v_fmac_f32_e32 v95, 0xba800000, v64
	v_fmac_f32_e32 v49, 0xba800000, v64
	v_pk_mov_b32 v[98:99], v[92:93], v[62:63] op_sel:[1,0]
	v_mov_b32_e32 v93, v63
	v_pk_mul_f32 v[62:63], v[46:47], v[46:47]
	v_pk_mul_f32 v[100:101], v[44:45], v[44:45]
	v_fmac_f32_e32 v48, 0xba800000, v64
	v_mov_b32_e32 v50, v49
	v_mov_b32_e32 v51, v95
	v_mov_b32_e32 v49, v94
	v_pk_add_f32 v[92:93], v[92:93], v[98:99]
	v_pk_mov_b32 v[98:99], v[100:101], v[62:63] op_sel:[1,0]
	v_mov_b32_e32 v101, v63
	v_pk_mul_f32 v[94:95], v[50:51], v[50:51]
	v_pk_mul_f32 v[96:97], v[48:49], v[48:49]
	v_pk_add_f32 v[62:63], v[98:99], v[100:101]
	v_fmac_f32_e32 v57, 0xba800000, v64
	v_pk_add_f32 v[98:99], v[62:63], v[62:63] op_sel_hi:[0,1]
	v_pk_mov_b32 v[62:63], v[96:97], v[94:95] op_sel:[1,0]
	v_mov_b32_e32 v97, v95
	v_fmac_f32_e32 v56, 0xba800000, v64
	v_fmac_f32_e32 v59, 0xba800000, v64
	v_fmac_f32_e32 v58, 0xba800000, v64
	v_fmac_f32_e32 v65, 0xba800000, v64
	v_fmac_f32_e32 v69, 0xba800000, v64
	v_fmac_f32_e32 v67, 0xba800000, v64
	v_fmac_f32_e32 v71, 0xba800000, v64
	v_mul_f32_e32 v64, v57, v57
	v_pk_add_f32 v[94:95], v[96:97], v[62:63]
	v_pk_fma_f32 v[100:101], v[56:57], v[56:57], v[64:65] op_sel_hi:[1,1,0]
	v_mul_f32_e32 v64, v59, v59
	v_mul_f32_e32 v68, v71, v71
	v_mul_f32_e32 v70, v67, v67
	v_mul_f32_e32 v72, v69, v69
	v_mul_f32_e32 v74, v65, v65
	v_pk_fma_f32 v[102:103], v[58:59], v[58:59], v[64:65] op_sel_hi:[1,1,0]
	v_pk_add_f32 v[92:93], v[92:93], v[92:93] op_sel:[0,1] op_sel_hi:[1,0]
	v_pk_add_f32 v[94:95], v[94:95], v[94:95] op_sel:[0,1] op_sel_hi:[1,0]
	v_mov_b32_e32 v101, v68
	v_mov_b32_e32 v103, v70
	v_mov_b32_e32 v93, v74
	v_mov_b32_e32 v95, v72
	v_pk_add_f32 v[100:101], v[100:101], v[102:103]
	v_pk_add_f32 v[92:93], v[92:93], v[94:95]
	v_fmac_f32_e32 v54, 0xba800000, v66
	v_pk_add_f32 v[92:93], v[100:101], v[92:93]
	v_fmac_f32_e32 v55, 0xba800000, v66
	v_fmac_f32_e32 v53, 0xba800000, v66
	v_add_f32_e32 v64, v92, v93
	v_fmac_f32_e32 v52, 0xba800000, v66
	v_mov_b32_e32 v62, v53
	v_mov_b32_e32 v63, v55
	v_mov_b32_e32 v53, v54
	ds_bpermute_b32 v68, v82, v64
	v_pk_mul_f32 v[96:97], v[62:63], v[62:63]
	v_pk_mul_f32 v[54:55], v[52:53], v[52:53]
	v_fmac_f32_e32 v60, 0xba800000, v66
	v_pk_mov_b32 v[92:93], v[54:55], v[96:97] op_sel:[1,0]
	v_mov_b32_e32 v55, v97
	v_pk_add_f32 v[54:55], v[92:93], v[54:55]
	v_fmac_f32_e32 v61, 0xba800000, v66
	v_pk_add_f32 v[54:55], v[54:55], v[54:55] op_sel_hi:[0,1]
	s_waitcnt lgkmcnt(0)
	v_add_f32_e32 v54, v64, v68
	ds_bpermute_b32 v64, v83, v54
	v_fmac_f32_e32 v80, 0xba800000, v66
	v_fmac_f32_e32 v81, 0xba800000, v66
	v_fmac_f32_e32 v73, 0xba800000, v66
	v_fmac_f32_e32 v77, 0xba800000, v66
	s_waitcnt lgkmcnt(0)
	v_add_f32_e32 v64, v54, v64
	ds_bpermute_b32 v68, v84, v64
	v_mul_f32_e32 v54, v60, v60
	v_pk_fma_f32 v[92:93], v[60:61], v[60:61], v[54:55] op_sel_hi:[1,1,0]
	v_mul_f32_e32 v54, v80, v80
	v_pk_fma_f32 v[94:95], v[80:81], v[80:81], v[54:55] op_sel_hi:[1,1,0]
	s_waitcnt lgkmcnt(0)
	v_add_f32_e32 v54, v64, v68
	ds_bpermute_b32 v64, v85, v54
	v_fmac_f32_e32 v75, 0xba800000, v66
	v_fmac_f32_e32 v79, 0xba800000, v66
	v_mul_f32_e32 v92, v79, v79
	v_mul_f32_e32 v94, v75, v75
	s_waitcnt lgkmcnt(0)
	v_add_f32_e32 v64, v54, v64
	ds_bpermute_b32 v66, v86, v64
	v_mul_f32_e32 v98, v77, v77
	v_mul_f32_e32 v54, v73, v73
	v_pk_add_f32 v[92:93], v[92:93], v[94:95]
	v_pk_add_f32 v[54:55], v[98:99], v[54:55]
	s_waitcnt lgkmcnt(0)
	v_add_f32_e32 v64, v64, v66
	ds_bpermute_b32 v66, v87, v64
	v_pk_add_f32 v[54:55], v[92:93], v[54:55]
	v_lshl_add_u64 v[96:97], v[38:39], 0, s[20:21]
	v_add_f32_e32 v54, v54, v55
	v_lshl_add_u64 v[98:99], v[38:39], 0, s[22:23]
	s_waitcnt lgkmcnt(0)
	v_add_f32_e32 v55, v64, v66
	ds_bpermute_b32 v66, v82, v54
	v_fmamk_f32 v55, v55, 0x3a800000, v89
	v_mul_f32_e32 v64, 0x4f800000, v55
	v_cmp_gt_f32_e32 vcc, s24, v55
	v_lshl_add_u64 v[92:93], v[32:33], 0, s[26:27]
	s_waitcnt lgkmcnt(0)
	v_add_f32_e32 v54, v54, v66
	ds_bpermute_b32 v66, v83, v54
	v_cndmask_b32_e32 v55, v55, v64, vcc
	v_sqrt_f32_e32 v64, v55
	v_lshl_add_u64 v[94:95], v[32:33], 0, s[28:29]
	s_waitcnt lgkmcnt(0)
	v_add_f32_e32 v54, v54, v66
	ds_bpermute_b32 v66, v84, v54
	v_add_u32_e32 v68, -1, v64
	v_fma_f32 v70, -v68, v64, v55
	v_cmp_ge_f32_e64 s[12:13], 0, v70
	v_add_u32_e32 v70, 1, v64
	s_waitcnt lgkmcnt(0)
	v_add_f32_e32 v54, v54, v66
	ds_bpermute_b32 v66, v85, v54
	v_cndmask_b32_e64 v68, v64, v68, s[12:13]
	v_fma_f32 v64, -v70, v64, v55
	v_cmp_lt_f32_e64 s[12:13], 0, v64
	s_waitcnt lgkmcnt(0)
	v_add_f32_e32 v54, v54, v66
	ds_bpermute_b32 v66, v86, v54
	v_cndmask_b32_e64 v64, v68, v70, s[12:13]
	v_mul_f32_e32 v68, 0x37800000, v64
	v_cndmask_b32_e32 v64, v64, v68, vcc
	v_cmp_class_f32_e32 vcc, v55, v90
	s_waitcnt lgkmcnt(0)
	v_add_f32_e32 v54, v54, v66
	ds_bpermute_b32 v66, v87, v54
	v_cndmask_b32_e32 v55, v64, v55, vcc
	v_div_scale_f32 v64, s[12:13], v55, v55, 1.0
	v_rcp_f32_e32 v68, v64
	s_waitcnt lgkmcnt(0)
	v_add_f32_e32 v54, v54, v66
	v_fmamk_f32 v54, v54, 0x3a800000, v89
	v_mul_f32_e32 v66, 0x4f800000, v54
	v_cmp_gt_f32_e64 s[12:13], s24, v54
	v_fma_f32 v70, -v64, v68, 1.0
	v_fmac_f32_e32 v68, v70, v68
	v_cndmask_b32_e64 v54, v54, v66, s[12:13]
	v_div_scale_f32 v70, vcc, 1.0, v55, 1.0
	v_sqrt_f32_e32 v66, v54
	v_mul_f32_e32 v72, v70, v68
	v_fma_f32 v74, -v64, v72, v70
	v_fmac_f32_e32 v72, v74, v68
	v_fma_f32 v64, -v64, v72, v70
	v_add_u32_e32 v70, -1, v66
	v_fma_f32 v74, -v70, v66, v54
	v_cmp_ge_f32_e64 s[14:15], 0, v74
	v_add_u32_e32 v74, 1, v66
	v_div_fmas_f32 v64, v64, v68, v72
	v_cndmask_b32_e64 v70, v66, v70, s[14:15]
	v_fma_f32 v66, -v74, v66, v54
	v_cmp_lt_f32_e64 s[14:15], 0, v66
	v_div_fixup_f32 v68, v64, v55, 1.0
	v_pk_mul_f32 v[40:41], v[40:41], v[68:69] op_sel_hi:[1,0]
	v_cndmask_b32_e64 v66, v70, v74, s[14:15]
	v_mul_f32_e32 v70, 0x37800000, v66
	v_cndmask_b32_e64 v66, v66, v70, s[12:13]
	v_cmp_class_f32_e64 s[12:13], v54, v90
	v_pk_fma_f32 v[40:41], v[0:1], v[40:41], v[8:9]
	v_pk_mul_f32 v[42:43], v[42:43], v[68:69] op_sel_hi:[1,0]
	v_cndmask_b32_e64 v54, v66, v54, s[12:13]
	v_div_scale_f32 v66, s[12:13], v54, v54, 1.0
	v_rcp_f32_e32 v70, v66
	v_pk_fma_f32 v[42:43], v[2:3], v[42:43], v[10:11]
	v_pk_mul_f32 v[48:49], v[48:49], v[68:69] op_sel_hi:[1,0]
	v_pk_mul_f32 v[56:57], v[68:69], v[56:57] op_sel_hi:[0,1]
	v_fma_f32 v55, -v66, v70, 1.0
	v_fmac_f32_e32 v70, v55, v70
	v_div_scale_f32 v55, vcc, 1.0, v54, 1.0
	v_mul_f32_e32 v64, v55, v70
	v_fma_f32 v72, -v66, v64, v55
	v_fmac_f32_e32 v64, v72, v70
	v_fma_f32 v55, -v66, v64, v55
	v_div_fmas_f32 v55, v55, v70, v64
	v_div_fixup_f32 v70, v55, v54, 1.0
	v_pk_mul_f32 v[44:45], v[44:45], v[70:71] op_sel_hi:[1,0]
	v_mov_b32_e32 v64, 0
	v_pk_mul_f32 v[54:55], v[46:47], v[70:71] op_sel_hi:[1,0]
	v_pk_fma_f32 v[46:47], v[0:1], v[44:45], v[8:9]
	v_cvt_pk_fp8_f32 v64, v40, v41
	v_mov_b32_e32 v66, 0
	v_cvt_pk_fp8_f32 v66, v46, v47
	v_pk_fma_f32 v[44:45], v[2:3], v[54:55], v[10:11]
	v_cvt_pk_fp8_f32 v64, v42, v43 op_sel:[0,0,1]
	v_cvt_pk_bf16_f32 v54, v40, v41
	v_cvt_pk_bf16_f32 v55, v42, v43
	v_cvt_pk_fp8_f32 v66, v44, v45 op_sel:[0,0,1]
	global_store_dwordx2 v[96:97], v[54:55], off
	v_cvt_pk_bf16_f32 v54, v46, v47
	v_cvt_pk_bf16_f32 v55, v44, v45
	global_store_dwordx2 v[98:99], v[54:55], off
	global_store_dword v[92:93], v64, off
	global_store_dword v[94:95], v66, off
	v_pk_mul_f32 v[54:55], v[50:51], v[68:69] op_sel_hi:[1,0]
	v_pk_fma_f32 v[50:51], v[4:5], v[48:49], v[12:13]
	v_pk_mul_f32 v[52:53], v[52:53], v[70:71] op_sel_hi:[1,0]
	v_mov_b32_e32 v64, 0
	v_pk_fma_f32 v[52:53], v[4:5], v[52:53], v[12:13]
	v_cvt_pk_fp8_f32 v64, v50, v51
	v_mov_b32_e32 v66, 0
	v_cvt_pk_fp8_f32 v66, v52, v53
	v_pk_fma_f32 v[54:55], v[6:7], v[54:55], v[14:15]
	v_pk_mul_f32 v[48:49], v[62:63], v[70:71] op_sel_hi:[1,0]
	v_cvt_pk_fp8_f32 v64, v54, v55 op_sel:[0,0,1]
	v_pk_fma_f32 v[48:49], v[6:7], v[48:49], v[14:15]
	v_cvt_pk_bf16_f32 v62, v50, v51
	v_cvt_pk_bf16_f32 v63, v54, v55
	v_cvt_pk_fp8_f32 v66, v48, v49 op_sel:[0,0,1]
	global_store_dwordx2 v[96:97], v[62:63], off offset:512
	v_cvt_pk_bf16_f32 v62, v52, v53
	v_cvt_pk_bf16_f32 v63, v48, v49
	global_store_dwordx2 v[98:99], v[62:63], off offset:512
	global_store_dword v[92:93], v64, off offset:256
	global_store_dword v[94:95], v66, off offset:256
	v_pk_fma_f32 v[62:63], v[16:17], v[56:57], v[24:25]
	v_pk_mul_f32 v[60:61], v[70:71], v[60:61] op_sel_hi:[0,1]
	v_mov_b32_e32 v64, 0
	v_pk_fma_f32 v[60:61], v[16:17], v[60:61], v[24:25]
	v_cvt_pk_fp8_f32 v64, v62, v63
	v_mov_b32_e32 v66, 0
	v_cvt_pk_fp8_f32 v66, v60, v61
	v_pk_mul_f32 v[58:59], v[68:69], v[58:59] op_sel_hi:[0,1]
	v_pk_fma_f32 v[58:59], v[18:19], v[58:59], v[26:27]
	v_pk_mul_f32 v[56:57], v[70:71], v[80:81] op_sel_hi:[0,1]
	v_pk_fma_f32 v[56:57], v[18:19], v[56:57], v[26:27]
	v_cvt_pk_fp8_f32 v64, v58, v59 op_sel:[0,0,1]
	v_cvt_pk_bf16_f32 v80, v62, v63
	v_cvt_pk_bf16_f32 v81, v58, v59
	v_cvt_pk_fp8_f32 v66, v56, v57 op_sel:[0,0,1]
	global_store_dwordx2 v[96:97], v[80:81], off offset:1024
	v_cvt_pk_bf16_f32 v80, v60, v61
	v_cvt_pk_bf16_f32 v81, v56, v57
	global_store_dwordx2 v[98:99], v[80:81], off offset:1024
	global_store_dword v[92:93], v64, off offset:512
	global_store_dword v[94:95], v66, off offset:512
	v_mov_b32_e32 v66, v71
	v_mov_b32_e32 v74, v79
	v_pk_mul_f32 v[66:67], v[68:69], v[66:67] op_sel_hi:[0,1]
	v_mov_b32_e32 v64, v69
	v_pk_mul_f32 v[74:75], v[70:71], v[74:75] op_sel_hi:[0,1]
	v_mov_b32_e32 v72, v77
	v_pk_mul_f32 v[64:65], v[68:69], v[64:65] op_sel_hi:[0,1]
	v_pk_fma_f32 v[68:69], v[20:21], v[66:67], v[28:29]
	v_pk_mul_f32 v[66:67], v[70:71], v[72:73] op_sel_hi:[0,1]
	v_pk_fma_f32 v[70:71], v[20:21], v[74:75], v[28:29]
	v_mov_b32_e32 v74, 0
	v_cvt_pk_fp8_f32 v74, v68, v69
	v_mov_b32_e32 v75, 0
	v_cvt_pk_fp8_f32 v75, v70, v71
	v_pk_fma_f32 v[64:65], v[22:23], v[64:65], v[30:31]
	v_pk_fma_f32 v[66:67], v[22:23], v[66:67], v[30:31]
	v_cvt_pk_fp8_f32 v74, v64, v65 op_sel:[0,0,1]
	v_cvt_pk_bf16_f32 v72, v68, v69
	v_cvt_pk_bf16_f32 v73, v64, v65
	v_cvt_pk_fp8_f32 v75, v66, v67 op_sel:[0,0,1]
	global_store_dwordx2 v[96:97], v[72:73], off offset:1536
	v_cvt_pk_bf16_f32 v72, v70, v71
	v_cvt_pk_bf16_f32 v73, v66, v67
	global_store_dwordx2 v[98:99], v[72:73], off offset:1536
	global_store_dword v[92:93], v74, off offset:768
	global_store_dword v[94:95], v75, off offset:768
	ds_read_b128 v[176:179], v88 offset:0
	ds_read_b128 v[180:183], v88 offset:1024
	ds_read_b128 v[184:187], v88 offset:2048
	ds_read_b128 v[188:191], v88 offset:3072
	ds_read_b128 v[192:195], v88 offset:4096
	ds_read_b128 v[196:199], v88 offset:5120
	ds_read_b128 v[200:203], v88 offset:6144
	ds_read_b128 v[204:207], v88 offset:7168
	s_waitcnt lgkmcnt(4)
	v_pk_mul_f32 v[208:209], v[40:41], v[176:177]
	v_pk_mul_f32 v[210:211], v[46:47], v[176:177]
	v_pk_fma_f32 v[208:209], v[42:43], v[178:179], v[208:209]
	v_pk_fma_f32 v[210:211], v[44:45], v[178:179], v[210:211]
	v_pk_fma_f32 v[208:209], v[50:51], v[180:181], v[208:209]
	v_pk_fma_f32 v[210:211], v[52:53], v[180:181], v[210:211]
	v_pk_fma_f32 v[208:209], v[54:55], v[182:183], v[208:209]
	v_pk_fma_f32 v[210:211], v[48:49], v[182:183], v[210:211]
	v_pk_fma_f32 v[208:209], v[62:63], v[184:185], v[208:209]
	v_pk_fma_f32 v[210:211], v[60:61], v[184:185], v[210:211]
	v_pk_fma_f32 v[208:209], v[58:59], v[186:187], v[208:209]
	v_pk_fma_f32 v[210:211], v[56:57], v[186:187], v[210:211]
	v_pk_fma_f32 v[208:209], v[68:69], v[188:189], v[208:209]
	v_pk_fma_f32 v[210:211], v[70:71], v[188:189], v[210:211]
	v_pk_fma_f32 v[208:209], v[64:65], v[190:191], v[208:209]
	v_pk_fma_f32 v[210:211], v[66:67], v[190:191], v[210:211]
	v_add_f32_e32 v142, v208, v209
	v_add_f32_e32 v143, v210, v211
	ds_read_b128 v[176:179], v88 offset:8192
	ds_read_b128 v[180:183], v88 offset:9216
	ds_read_b128 v[184:187], v88 offset:10240
	ds_read_b128 v[188:191], v88 offset:11264
	s_waitcnt lgkmcnt(4)
	v_pk_mul_f32 v[208:209], v[40:41], v[192:193]
	v_pk_mul_f32 v[210:211], v[46:47], v[192:193]
	v_pk_fma_f32 v[208:209], v[42:43], v[194:195], v[208:209]
	v_pk_fma_f32 v[210:211], v[44:45], v[194:195], v[210:211]
	v_pk_fma_f32 v[208:209], v[50:51], v[196:197], v[208:209]
	v_pk_fma_f32 v[210:211], v[52:53], v[196:197], v[210:211]
	v_pk_fma_f32 v[208:209], v[54:55], v[198:199], v[208:209]
	v_pk_fma_f32 v[210:211], v[48:49], v[198:199], v[210:211]
	v_pk_fma_f32 v[208:209], v[62:63], v[200:201], v[208:209]
	v_pk_fma_f32 v[210:211], v[60:61], v[200:201], v[210:211]
	v_pk_fma_f32 v[208:209], v[58:59], v[202:203], v[208:209]
	v_pk_fma_f32 v[210:211], v[56:57], v[202:203], v[210:211]
	v_pk_fma_f32 v[208:209], v[68:69], v[204:205], v[208:209]
	v_pk_fma_f32 v[210:211], v[70:71], v[204:205], v[210:211]
	v_pk_fma_f32 v[208:209], v[64:65], v[206:207], v[208:209]
	v_pk_fma_f32 v[210:211], v[66:67], v[206:207], v[210:211]
	v_add_f32_e32 v144, v208, v209
	v_add_f32_e32 v145, v210, v211
	ds_read_b128 v[192:195], v88 offset:12288
	ds_read_b128 v[196:199], v88 offset:13312
	ds_read_b128 v[200:203], v88 offset:14336
	ds_read_b128 v[204:207], v88 offset:15360
	s_waitcnt lgkmcnt(4)
	v_pk_mul_f32 v[208:209], v[40:41], v[176:177]
	v_pk_mul_f32 v[210:211], v[46:47], v[176:177]
	v_pk_fma_f32 v[208:209], v[42:43], v[178:179], v[208:209]
	v_pk_fma_f32 v[210:211], v[44:45], v[178:179], v[210:211]
	v_pk_fma_f32 v[208:209], v[50:51], v[180:181], v[208:209]
	v_pk_fma_f32 v[210:211], v[52:53], v[180:181], v[210:211]
	v_pk_fma_f32 v[208:209], v[54:55], v[182:183], v[208:209]
	v_pk_fma_f32 v[210:211], v[48:49], v[182:183], v[210:211]
	v_pk_fma_f32 v[208:209], v[62:63], v[184:185], v[208:209]
	v_pk_fma_f32 v[210:211], v[60:61], v[184:185], v[210:211]
	v_pk_fma_f32 v[208:209], v[58:59], v[186:187], v[208:209]
	v_pk_fma_f32 v[210:211], v[56:57], v[186:187], v[210:211]
	v_pk_fma_f32 v[208:209], v[68:69], v[188:189], v[208:209]
	v_pk_fma_f32 v[210:211], v[70:71], v[188:189], v[210:211]
	v_pk_fma_f32 v[208:209], v[64:65], v[190:191], v[208:209]
	v_pk_fma_f32 v[210:211], v[66:67], v[190:191], v[210:211]
	v_add_f32_e32 v146, v208, v209
	v_add_f32_e32 v147, v210, v211
	ds_read_b128 v[176:179], v88 offset:16384
	ds_read_b128 v[180:183], v88 offset:17408
	ds_read_b128 v[184:187], v88 offset:18432
	ds_read_b128 v[188:191], v88 offset:19456
	s_waitcnt lgkmcnt(4)
	v_pk_mul_f32 v[208:209], v[40:41], v[192:193]
	v_pk_mul_f32 v[210:211], v[46:47], v[192:193]
	v_pk_fma_f32 v[208:209], v[42:43], v[194:195], v[208:209]
	v_pk_fma_f32 v[210:211], v[44:45], v[194:195], v[210:211]
	v_pk_fma_f32 v[208:209], v[50:51], v[196:197], v[208:209]
	v_pk_fma_f32 v[210:211], v[52:53], v[196:197], v[210:211]
	v_pk_fma_f32 v[208:209], v[54:55], v[198:199], v[208:209]
	v_pk_fma_f32 v[210:211], v[48:49], v[198:199], v[210:211]
	v_pk_fma_f32 v[208:209], v[62:63], v[200:201], v[208:209]
	v_pk_fma_f32 v[210:211], v[60:61], v[200:201], v[210:211]
	v_pk_fma_f32 v[208:209], v[58:59], v[202:203], v[208:209]
	v_pk_fma_f32 v[210:211], v[56:57], v[202:203], v[210:211]
	v_pk_fma_f32 v[208:209], v[68:69], v[204:205], v[208:209]
	v_pk_fma_f32 v[210:211], v[70:71], v[204:205], v[210:211]
	v_pk_fma_f32 v[208:209], v[64:65], v[206:207], v[208:209]
	v_pk_fma_f32 v[210:211], v[66:67], v[206:207], v[210:211]
	v_add_f32_e32 v148, v208, v209
	v_add_f32_e32 v149, v210, v211
	ds_read_b128 v[192:195], v88 offset:20480
	ds_read_b128 v[196:199], v88 offset:21504
	ds_read_b128 v[200:203], v88 offset:22528
	ds_read_b128 v[204:207], v88 offset:23552
	s_waitcnt lgkmcnt(4)
	v_pk_mul_f32 v[208:209], v[40:41], v[176:177]
	v_pk_mul_f32 v[210:211], v[46:47], v[176:177]
	v_pk_fma_f32 v[208:209], v[42:43], v[178:179], v[208:209]
	v_pk_fma_f32 v[210:211], v[44:45], v[178:179], v[210:211]
	v_pk_fma_f32 v[208:209], v[50:51], v[180:181], v[208:209]
	v_pk_fma_f32 v[210:211], v[52:53], v[180:181], v[210:211]
	v_pk_fma_f32 v[208:209], v[54:55], v[182:183], v[208:209]
	v_pk_fma_f32 v[210:211], v[48:49], v[182:183], v[210:211]
	v_pk_fma_f32 v[208:209], v[62:63], v[184:185], v[208:209]
	v_pk_fma_f32 v[210:211], v[60:61], v[184:185], v[210:211]
	v_pk_fma_f32 v[208:209], v[58:59], v[186:187], v[208:209]
	v_pk_fma_f32 v[210:211], v[56:57], v[186:187], v[210:211]
	v_pk_fma_f32 v[208:209], v[68:69], v[188:189], v[208:209]
	v_pk_fma_f32 v[210:211], v[70:71], v[188:189], v[210:211]
	v_pk_fma_f32 v[208:209], v[64:65], v[190:191], v[208:209]
	v_pk_fma_f32 v[210:211], v[66:67], v[190:191], v[210:211]
	v_add_f32_e32 v150, v208, v209
	v_add_f32_e32 v151, v210, v211
	ds_read_b128 v[176:179], v88 offset:24576
	ds_read_b128 v[180:183], v88 offset:25600
	ds_read_b128 v[184:187], v88 offset:26624
	ds_read_b128 v[188:191], v88 offset:27648
	s_waitcnt lgkmcnt(4)
	v_pk_mul_f32 v[208:209], v[40:41], v[192:193]
	v_pk_mul_f32 v[210:211], v[46:47], v[192:193]
	v_pk_fma_f32 v[208:209], v[42:43], v[194:195], v[208:209]
	v_pk_fma_f32 v[210:211], v[44:45], v[194:195], v[210:211]
	v_pk_fma_f32 v[208:209], v[50:51], v[196:197], v[208:209]
	v_pk_fma_f32 v[210:211], v[52:53], v[196:197], v[210:211]
	v_pk_fma_f32 v[208:209], v[54:55], v[198:199], v[208:209]
	v_pk_fma_f32 v[210:211], v[48:49], v[198:199], v[210:211]
	v_pk_fma_f32 v[208:209], v[62:63], v[200:201], v[208:209]
	v_pk_fma_f32 v[210:211], v[60:61], v[200:201], v[210:211]
	v_pk_fma_f32 v[208:209], v[58:59], v[202:203], v[208:209]
	v_pk_fma_f32 v[210:211], v[56:57], v[202:203], v[210:211]
	v_pk_fma_f32 v[208:209], v[68:69], v[204:205], v[208:209]
	v_pk_fma_f32 v[210:211], v[70:71], v[204:205], v[210:211]
	v_pk_fma_f32 v[208:209], v[64:65], v[206:207], v[208:209]
	v_pk_fma_f32 v[210:211], v[66:67], v[206:207], v[210:211]
	v_add_f32_e32 v152, v208, v209
	v_add_f32_e32 v153, v210, v211
	ds_read_b128 v[192:195], v88 offset:28672
	ds_read_b128 v[196:199], v88 offset:29696
	ds_read_b128 v[200:203], v88 offset:30720
	ds_read_b128 v[204:207], v88 offset:31744
	s_waitcnt lgkmcnt(4)
	v_pk_mul_f32 v[208:209], v[40:41], v[176:177]
	v_pk_mul_f32 v[210:211], v[46:47], v[176:177]
	v_pk_fma_f32 v[208:209], v[42:43], v[178:179], v[208:209]
	v_pk_fma_f32 v[210:211], v[44:45], v[178:179], v[210:211]
	v_pk_fma_f32 v[208:209], v[50:51], v[180:181], v[208:209]
	v_pk_fma_f32 v[210:211], v[52:53], v[180:181], v[210:211]
	v_pk_fma_f32 v[208:209], v[54:55], v[182:183], v[208:209]
	v_pk_fma_f32 v[210:211], v[48:49], v[182:183], v[210:211]
	v_pk_fma_f32 v[208:209], v[62:63], v[184:185], v[208:209]
	v_pk_fma_f32 v[210:211], v[60:61], v[184:185], v[210:211]
	v_pk_fma_f32 v[208:209], v[58:59], v[186:187], v[208:209]
	v_pk_fma_f32 v[210:211], v[56:57], v[186:187], v[210:211]
	v_pk_fma_f32 v[208:209], v[68:69], v[188:189], v[208:209]
	v_pk_fma_f32 v[210:211], v[70:71], v[188:189], v[210:211]
	v_pk_fma_f32 v[208:209], v[64:65], v[190:191], v[208:209]
	v_pk_fma_f32 v[210:211], v[66:67], v[190:191], v[210:211]
	v_add_f32_e32 v154, v208, v209
	v_add_f32_e32 v155, v210, v211
	ds_read_b128 v[176:179], v88 offset:32768
	ds_read_b128 v[180:183], v88 offset:33792
	ds_read_b128 v[184:187], v88 offset:34816
	ds_read_b128 v[188:191], v88 offset:35840
	s_waitcnt lgkmcnt(4)
	v_pk_mul_f32 v[208:209], v[40:41], v[192:193]
	v_pk_mul_f32 v[210:211], v[46:47], v[192:193]
	v_pk_fma_f32 v[208:209], v[42:43], v[194:195], v[208:209]
	v_pk_fma_f32 v[210:211], v[44:45], v[194:195], v[210:211]
	v_pk_fma_f32 v[208:209], v[50:51], v[196:197], v[208:209]
	v_pk_fma_f32 v[210:211], v[52:53], v[196:197], v[210:211]
	v_pk_fma_f32 v[208:209], v[54:55], v[198:199], v[208:209]
	v_pk_fma_f32 v[210:211], v[48:49], v[198:199], v[210:211]
	v_pk_fma_f32 v[208:209], v[62:63], v[200:201], v[208:209]
	v_pk_fma_f32 v[210:211], v[60:61], v[200:201], v[210:211]
	v_pk_fma_f32 v[208:209], v[58:59], v[202:203], v[208:209]
	v_pk_fma_f32 v[210:211], v[56:57], v[202:203], v[210:211]
	v_pk_fma_f32 v[208:209], v[68:69], v[204:205], v[208:209]
	v_pk_fma_f32 v[210:211], v[70:71], v[204:205], v[210:211]
	v_pk_fma_f32 v[208:209], v[64:65], v[206:207], v[208:209]
	v_pk_fma_f32 v[210:211], v[66:67], v[206:207], v[210:211]
	v_add_f32_e32 v156, v208, v209
	v_add_f32_e32 v157, v210, v211
	ds_read_b128 v[192:195], v88 offset:36864
	ds_read_b128 v[196:199], v88 offset:37888
	ds_read_b128 v[200:203], v88 offset:38912
	ds_read_b128 v[204:207], v88 offset:39936
	s_waitcnt lgkmcnt(4)
	v_pk_mul_f32 v[208:209], v[40:41], v[176:177]
	v_pk_mul_f32 v[210:211], v[46:47], v[176:177]
	v_pk_fma_f32 v[208:209], v[42:43], v[178:179], v[208:209]
	v_pk_fma_f32 v[210:211], v[44:45], v[178:179], v[210:211]
	v_pk_fma_f32 v[208:209], v[50:51], v[180:181], v[208:209]
	v_pk_fma_f32 v[210:211], v[52:53], v[180:181], v[210:211]
	v_pk_fma_f32 v[208:209], v[54:55], v[182:183], v[208:209]
	v_pk_fma_f32 v[210:211], v[48:49], v[182:183], v[210:211]
	v_pk_fma_f32 v[208:209], v[62:63], v[184:185], v[208:209]
	v_pk_fma_f32 v[210:211], v[60:61], v[184:185], v[210:211]
	v_pk_fma_f32 v[208:209], v[58:59], v[186:187], v[208:209]
	v_pk_fma_f32 v[210:211], v[56:57], v[186:187], v[210:211]
	v_pk_fma_f32 v[208:209], v[68:69], v[188:189], v[208:209]
	v_pk_fma_f32 v[210:211], v[70:71], v[188:189], v[210:211]
	v_pk_fma_f32 v[208:209], v[64:65], v[190:191], v[208:209]
	v_pk_fma_f32 v[210:211], v[66:67], v[190:191], v[210:211]
	v_add_f32_e32 v158, v208, v209
	v_add_f32_e32 v159, v210, v211
	ds_read_b128 v[176:179], v88 offset:40960
	ds_read_b128 v[180:183], v88 offset:41984
	ds_read_b128 v[184:187], v88 offset:43008
	ds_read_b128 v[188:191], v88 offset:44032
	s_waitcnt lgkmcnt(4)
	v_pk_mul_f32 v[208:209], v[40:41], v[192:193]
	v_pk_mul_f32 v[210:211], v[46:47], v[192:193]
	v_pk_fma_f32 v[208:209], v[42:43], v[194:195], v[208:209]
	v_pk_fma_f32 v[210:211], v[44:45], v[194:195], v[210:211]
	v_pk_fma_f32 v[208:209], v[50:51], v[196:197], v[208:209]
	v_pk_fma_f32 v[210:211], v[52:53], v[196:197], v[210:211]
	v_pk_fma_f32 v[208:209], v[54:55], v[198:199], v[208:209]
	v_pk_fma_f32 v[210:211], v[48:49], v[198:199], v[210:211]
	v_pk_fma_f32 v[208:209], v[62:63], v[200:201], v[208:209]
	v_pk_fma_f32 v[210:211], v[60:61], v[200:201], v[210:211]
	v_pk_fma_f32 v[208:209], v[58:59], v[202:203], v[208:209]
	v_pk_fma_f32 v[210:211], v[56:57], v[202:203], v[210:211]
	v_pk_fma_f32 v[208:209], v[68:69], v[204:205], v[208:209]
	v_pk_fma_f32 v[210:211], v[70:71], v[204:205], v[210:211]
	v_pk_fma_f32 v[208:209], v[64:65], v[206:207], v[208:209]
	v_pk_fma_f32 v[210:211], v[66:67], v[206:207], v[210:211]
	v_add_f32_e32 v160, v208, v209
	v_add_f32_e32 v161, v210, v211
	ds_read_b128 v[192:195], v88 offset:45056
	ds_read_b128 v[196:199], v88 offset:46080
	ds_read_b128 v[200:203], v88 offset:47104
	ds_read_b128 v[204:207], v88 offset:48128
	s_waitcnt lgkmcnt(4)
	v_pk_mul_f32 v[208:209], v[40:41], v[176:177]
	v_pk_mul_f32 v[210:211], v[46:47], v[176:177]
	v_pk_fma_f32 v[208:209], v[42:43], v[178:179], v[208:209]
	v_pk_fma_f32 v[210:211], v[44:45], v[178:179], v[210:211]
	v_pk_fma_f32 v[208:209], v[50:51], v[180:181], v[208:209]
	v_pk_fma_f32 v[210:211], v[52:53], v[180:181], v[210:211]
	v_pk_fma_f32 v[208:209], v[54:55], v[182:183], v[208:209]
	v_pk_fma_f32 v[210:211], v[48:49], v[182:183], v[210:211]
	v_pk_fma_f32 v[208:209], v[62:63], v[184:185], v[208:209]
	v_pk_fma_f32 v[210:211], v[60:61], v[184:185], v[210:211]
	v_pk_fma_f32 v[208:209], v[58:59], v[186:187], v[208:209]
	v_pk_fma_f32 v[210:211], v[56:57], v[186:187], v[210:211]
	v_pk_fma_f32 v[208:209], v[68:69], v[188:189], v[208:209]
	v_pk_fma_f32 v[210:211], v[70:71], v[188:189], v[210:211]
	v_pk_fma_f32 v[208:209], v[64:65], v[190:191], v[208:209]
	v_pk_fma_f32 v[210:211], v[66:67], v[190:191], v[210:211]
	v_add_f32_e32 v162, v208, v209
	v_add_f32_e32 v163, v210, v211
	ds_read_b128 v[176:179], v88 offset:49152
	ds_read_b128 v[180:183], v88 offset:50176
	ds_read_b128 v[184:187], v88 offset:51200
	ds_read_b128 v[188:191], v88 offset:52224
	s_waitcnt lgkmcnt(4)
	v_pk_mul_f32 v[208:209], v[40:41], v[192:193]
	v_pk_mul_f32 v[210:211], v[46:47], v[192:193]
	v_pk_fma_f32 v[208:209], v[42:43], v[194:195], v[208:209]
	v_pk_fma_f32 v[210:211], v[44:45], v[194:195], v[210:211]
	v_pk_fma_f32 v[208:209], v[50:51], v[196:197], v[208:209]
	v_pk_fma_f32 v[210:211], v[52:53], v[196:197], v[210:211]
	v_pk_fma_f32 v[208:209], v[54:55], v[198:199], v[208:209]
	v_pk_fma_f32 v[210:211], v[48:49], v[198:199], v[210:211]
	v_pk_fma_f32 v[208:209], v[62:63], v[200:201], v[208:209]
	v_pk_fma_f32 v[210:211], v[60:61], v[200:201], v[210:211]
	v_pk_fma_f32 v[208:209], v[58:59], v[202:203], v[208:209]
	v_pk_fma_f32 v[210:211], v[56:57], v[202:203], v[210:211]
	v_pk_fma_f32 v[208:209], v[68:69], v[204:205], v[208:209]
	v_pk_fma_f32 v[210:211], v[70:71], v[204:205], v[210:211]
	v_pk_fma_f32 v[208:209], v[64:65], v[206:207], v[208:209]
	v_pk_fma_f32 v[210:211], v[66:67], v[206:207], v[210:211]
	v_add_f32_e32 v164, v208, v209
	v_add_f32_e32 v165, v210, v211
	ds_read_b128 v[192:195], v88 offset:53248
	ds_read_b128 v[196:199], v88 offset:54272
	ds_read_b128 v[200:203], v88 offset:55296
	ds_read_b128 v[204:207], v88 offset:56320
	s_waitcnt lgkmcnt(4)
	v_pk_mul_f32 v[208:209], v[40:41], v[176:177]
	v_pk_mul_f32 v[210:211], v[46:47], v[176:177]
	v_pk_fma_f32 v[208:209], v[42:43], v[178:179], v[208:209]
	v_pk_fma_f32 v[210:211], v[44:45], v[178:179], v[210:211]
	v_pk_fma_f32 v[208:209], v[50:51], v[180:181], v[208:209]
	v_pk_fma_f32 v[210:211], v[52:53], v[180:181], v[210:211]
	v_pk_fma_f32 v[208:209], v[54:55], v[182:183], v[208:209]
	v_pk_fma_f32 v[210:211], v[48:49], v[182:183], v[210:211]
	v_pk_fma_f32 v[208:209], v[62:63], v[184:185], v[208:209]
	v_pk_fma_f32 v[210:211], v[60:61], v[184:185], v[210:211]
	v_pk_fma_f32 v[208:209], v[58:59], v[186:187], v[208:209]
	v_pk_fma_f32 v[210:211], v[56:57], v[186:187], v[210:211]
	v_pk_fma_f32 v[208:209], v[68:69], v[188:189], v[208:209]
	v_pk_fma_f32 v[210:211], v[70:71], v[188:189], v[210:211]
	v_pk_fma_f32 v[208:209], v[64:65], v[190:191], v[208:209]
	v_pk_fma_f32 v[210:211], v[66:67], v[190:191], v[210:211]
	v_add_f32_e32 v166, v208, v209
	v_add_f32_e32 v167, v210, v211
	ds_read_b128 v[176:179], v88 offset:57344
	ds_read_b128 v[180:183], v88 offset:58368
	ds_read_b128 v[184:187], v88 offset:59392
	ds_read_b128 v[188:191], v88 offset:60416
	s_waitcnt lgkmcnt(4)
	v_pk_mul_f32 v[208:209], v[40:41], v[192:193]
	v_pk_mul_f32 v[210:211], v[46:47], v[192:193]
	v_pk_fma_f32 v[208:209], v[42:43], v[194:195], v[208:209]
	v_pk_fma_f32 v[210:211], v[44:45], v[194:195], v[210:211]
	v_pk_fma_f32 v[208:209], v[50:51], v[196:197], v[208:209]
	v_pk_fma_f32 v[210:211], v[52:53], v[196:197], v[210:211]
	v_pk_fma_f32 v[208:209], v[54:55], v[198:199], v[208:209]
	v_pk_fma_f32 v[210:211], v[48:49], v[198:199], v[210:211]
	v_pk_fma_f32 v[208:209], v[62:63], v[200:201], v[208:209]
	v_pk_fma_f32 v[210:211], v[60:61], v[200:201], v[210:211]
	v_pk_fma_f32 v[208:209], v[58:59], v[202:203], v[208:209]
	v_pk_fma_f32 v[210:211], v[56:57], v[202:203], v[210:211]
	v_pk_fma_f32 v[208:209], v[68:69], v[204:205], v[208:209]
	v_pk_fma_f32 v[210:211], v[70:71], v[204:205], v[210:211]
	v_pk_fma_f32 v[208:209], v[64:65], v[206:207], v[208:209]
	v_pk_fma_f32 v[210:211], v[66:67], v[206:207], v[210:211]
	v_add_f32_e32 v168, v208, v209
	v_add_f32_e32 v169, v210, v211
	ds_read_b128 v[192:195], v88 offset:61440
	ds_read_b128 v[196:199], v88 offset:62464
	ds_read_b128 v[200:203], v88 offset:63488
	ds_read_b128 v[204:207], v88 offset:64512
	s_waitcnt lgkmcnt(4)
	v_pk_mul_f32 v[208:209], v[40:41], v[176:177]
	v_pk_mul_f32 v[210:211], v[46:47], v[176:177]
	v_pk_fma_f32 v[208:209], v[42:43], v[178:179], v[208:209]
	v_pk_fma_f32 v[210:211], v[44:45], v[178:179], v[210:211]
	v_pk_fma_f32 v[208:209], v[50:51], v[180:181], v[208:209]
	v_pk_fma_f32 v[210:211], v[52:53], v[180:181], v[210:211]
	v_pk_fma_f32 v[208:209], v[54:55], v[182:183], v[208:209]
	v_pk_fma_f32 v[210:211], v[48:49], v[182:183], v[210:211]
	v_pk_fma_f32 v[208:209], v[62:63], v[184:185], v[208:209]
	v_pk_fma_f32 v[210:211], v[60:61], v[184:185], v[210:211]
	v_pk_fma_f32 v[208:209], v[58:59], v[186:187], v[208:209]
	v_pk_fma_f32 v[210:211], v[56:57], v[186:187], v[210:211]
	v_pk_fma_f32 v[208:209], v[68:69], v[188:189], v[208:209]
	v_pk_fma_f32 v[210:211], v[70:71], v[188:189], v[210:211]
	v_pk_fma_f32 v[208:209], v[64:65], v[190:191], v[208:209]
	v_pk_fma_f32 v[210:211], v[66:67], v[190:191], v[210:211]
	v_add_f32_e32 v170, v208, v209
	v_add_f32_e32 v171, v210, v211
	s_waitcnt lgkmcnt(0)
	v_pk_mul_f32 v[208:209], v[40:41], v[192:193]
	v_pk_mul_f32 v[210:211], v[46:47], v[192:193]
	v_pk_fma_f32 v[208:209], v[42:43], v[194:195], v[208:209]
	v_pk_fma_f32 v[210:211], v[44:45], v[194:195], v[210:211]
	v_pk_fma_f32 v[208:209], v[50:51], v[196:197], v[208:209]
	v_pk_fma_f32 v[210:211], v[52:53], v[196:197], v[210:211]
	v_pk_fma_f32 v[208:209], v[54:55], v[198:199], v[208:209]
	v_pk_fma_f32 v[210:211], v[48:49], v[198:199], v[210:211]
	v_pk_fma_f32 v[208:209], v[62:63], v[200:201], v[208:209]
	v_pk_fma_f32 v[210:211], v[60:61], v[200:201], v[210:211]
	v_pk_fma_f32 v[208:209], v[58:59], v[202:203], v[208:209]
	v_pk_fma_f32 v[210:211], v[56:57], v[202:203], v[210:211]
	v_pk_fma_f32 v[208:209], v[68:69], v[204:205], v[208:209]
	v_pk_fma_f32 v[210:211], v[70:71], v[204:205], v[210:211]
	v_pk_fma_f32 v[208:209], v[64:65], v[206:207], v[208:209]
	v_pk_fma_f32 v[210:211], v[66:67], v[206:207], v[210:211]
	v_add_f32_e32 v172, v208, v209
	v_add_f32_e32 v173, v210, v211
	v_cndmask_b32_e64 v43, v142, v158, s[0:1]
	ds_bpermute_b32 v43, v82, v43
	v_cndmask_b32_e64 v45, v144, v160, s[0:1]
	ds_bpermute_b32 v45, v82, v45
	v_cndmask_b32_e64 v46, v146, v162, s[0:1]
	ds_bpermute_b32 v46, v82, v46
	v_cndmask_b32_e64 v44, v158, v142, s[0:1]
	s_waitcnt lgkmcnt(2)
	v_add_f32_e32 v43, v44, v43
	v_cndmask_b32_e64 v44, v160, v144, s[0:1]
	s_waitcnt lgkmcnt(1)
	v_add_f32_e32 v44, v44, v45
	v_cndmask_b32_e64 v45, v162, v146, s[0:1]
	s_waitcnt lgkmcnt(0)
	v_add_f32_e32 v45, v45, v46
	v_cndmask_b32_e64 v46, v148, v164, s[0:1]
	ds_bpermute_b32 v46, v82, v46
	v_cndmask_b32_e64 v48, v150, v166, s[0:1]
	ds_bpermute_b32 v48, v82, v48
	v_cndmask_b32_e64 v49, v152, v168, s[0:1]
	ds_bpermute_b32 v49, v82, v49
	v_cndmask_b32_e64 v47, v164, v148, s[0:1]
	s_waitcnt lgkmcnt(2)
	v_add_f32_e32 v46, v47, v46
	v_cndmask_b32_e64 v47, v166, v150, s[0:1]
	s_waitcnt lgkmcnt(1)
	v_add_f32_e32 v47, v47, v48
	v_cndmask_b32_e64 v48, v168, v152, s[0:1]
	s_waitcnt lgkmcnt(0)
	v_add_f32_e32 v48, v48, v49
	v_cndmask_b32_e64 v49, v154, v170, s[0:1]
	ds_bpermute_b32 v49, v82, v49
	v_cndmask_b32_e64 v51, v156, v172, s[0:1]
	ds_bpermute_b32 v51, v82, v51
	v_cndmask_b32_e64 v50, v170, v154, s[0:1]
	v_cndmask_b32_e64 v41, v172, v156, s[0:1]
	s_waitcnt lgkmcnt(1)
	v_add_f32_e32 v49, v50, v49
	v_cndmask_b32_e64 v52, v43, v47, s[4:5]
	s_waitcnt lgkmcnt(0)
	v_add_f32_e32 v41, v41, v51
	v_cndmask_b32_e64 v43, v47, v43, s[4:5]
	v_cndmask_b32_e64 v47, v44, v48, s[4:5]
	v_cndmask_b32_e64 v44, v48, v44, s[4:5]
	v_cndmask_b32_e64 v48, v45, v49, s[4:5]
	ds_bpermute_b32 v52, v83, v52
	ds_bpermute_b32 v48, v83, v48
	v_cndmask_b32_e64 v50, v46, v41, s[4:5]
	ds_bpermute_b32 v47, v83, v47
	ds_bpermute_b32 v50, v83, v50
	v_cndmask_b32_e64 v45, v49, v45, s[4:5]
	s_waitcnt lgkmcnt(3)
	v_add_f32_e32 v43, v43, v52
	s_waitcnt lgkmcnt(2)
	v_add_f32_e32 v45, v45, v48
	v_cndmask_b32_e64 v41, v41, v46, s[4:5]
	s_waitcnt lgkmcnt(1)
	v_add_f32_e32 v44, v44, v47
	s_waitcnt lgkmcnt(0)
	v_add_f32_e32 v41, v41, v50
	v_cndmask_b32_e64 v46, v43, v45, s[6:7]
	ds_bpermute_b32 v46, v84, v46
	v_cndmask_b32_e64 v47, v44, v41, s[6:7]
	ds_bpermute_b32 v47, v84, v47
	v_cndmask_b32_e64 v42, v45, v43, s[6:7]
	v_cndmask_b32_e64 v41, v41, v44, s[6:7]
	v_cndmask_b32_e64 v44, v143, v159, s[0:1]
	s_waitcnt lgkmcnt(1)
	v_add_f32_e32 v42, v42, v46
	ds_bpermute_b32 v44, v82, v44
	v_cndmask_b32_e64 v46, v145, v161, s[0:1]
	s_waitcnt lgkmcnt(1)
	v_add_f32_e32 v41, v41, v47
	ds_bpermute_b32 v46, v82, v46
	v_cndmask_b32_e64 v47, v147, v163, s[0:1]
	ds_bpermute_b32 v47, v82, v47
	v_cndmask_b32_e64 v45, v159, v143, s[0:1]
	s_waitcnt lgkmcnt(2)
	v_add_f32_e32 v44, v45, v44
	v_cndmask_b32_e64 v45, v161, v145, s[0:1]
	s_waitcnt lgkmcnt(1)
	v_add_f32_e32 v45, v45, v46
	v_cndmask_b32_e64 v46, v163, v147, s[0:1]
	s_waitcnt lgkmcnt(0)
	v_add_f32_e32 v46, v46, v47
	v_cndmask_b32_e64 v47, v149, v165, s[0:1]
	ds_bpermute_b32 v47, v82, v47
	v_cndmask_b32_e64 v49, v151, v167, s[0:1]
	ds_bpermute_b32 v49, v82, v49
	v_cndmask_b32_e64 v50, v153, v169, s[0:1]
	ds_bpermute_b32 v50, v82, v50
	v_cndmask_b32_e64 v48, v165, v149, s[0:1]
	s_waitcnt lgkmcnt(2)
	v_add_f32_e32 v47, v48, v47
	v_cndmask_b32_e64 v48, v167, v151, s[0:1]
	s_waitcnt lgkmcnt(1)
	v_add_f32_e32 v48, v48, v49
	v_cndmask_b32_e64 v49, v169, v153, s[0:1]
	s_waitcnt lgkmcnt(0)
	v_add_f32_e32 v49, v49, v50
	v_cndmask_b32_e64 v50, v155, v171, s[0:1]
	v_cndmask_b32_e64 v52, v157, v173, s[0:1]
	ds_bpermute_b32 v50, v82, v50
	ds_bpermute_b32 v52, v82, v52
	v_cndmask_b32_e64 v51, v171, v155, s[0:1]
	v_cndmask_b32_e64 v40, v173, v157, s[0:1]
	v_cndmask_b32_e64 v53, v44, v48, s[4:5]
	s_waitcnt lgkmcnt(1)
	v_add_f32_e32 v50, v51, v50
	s_waitcnt lgkmcnt(0)
	v_add_f32_e32 v40, v40, v52
	v_cndmask_b32_e64 v44, v48, v44, s[4:5]
	v_cndmask_b32_e64 v48, v45, v49, s[4:5]
	v_cndmask_b32_e64 v45, v49, v45, s[4:5]
	v_cndmask_b32_e64 v49, v46, v50, s[4:5]
	v_cndmask_b32_e64 v51, v47, v40, s[4:5]
	ds_bpermute_b32 v53, v83, v53
	ds_bpermute_b32 v48, v83, v48
	ds_bpermute_b32 v49, v83, v49
	ds_bpermute_b32 v51, v83, v51
	v_cndmask_b32_e64 v46, v50, v46, s[4:5]
	v_cndmask_b32_e64 v40, v40, v47, s[4:5]
	s_waitcnt lgkmcnt(3)
	v_add_f32_e32 v44, v44, v53
	s_waitcnt lgkmcnt(2)
	v_add_f32_e32 v45, v45, v48
	s_waitcnt lgkmcnt(1)
	v_add_f32_e32 v46, v46, v49
	s_waitcnt lgkmcnt(0)
	v_add_f32_e32 v40, v40, v51
	v_cndmask_b32_e64 v47, v44, v46, s[6:7]
	v_cndmask_b32_e64 v48, v45, v40, s[6:7]
	ds_bpermute_b32 v47, v84, v47
	ds_bpermute_b32 v48, v84, v48
	v_cndmask_b32_e64 v44, v46, v44, s[6:7]
	v_cndmask_b32_e64 v40, v40, v45, s[6:7]
	v_cndmask_b32_e64 v43, v42, v41, s[8:9]
	s_waitcnt lgkmcnt(1)
	v_add_f32_e32 v44, v44, v47
	s_waitcnt lgkmcnt(0)
	v_add_f32_e32 v40, v40, v48
	ds_bpermute_b32 v43, v85, v43
	v_cndmask_b32_e64 v45, v44, v40, s[8:9]
	ds_bpermute_b32 v45, v85, v45
	v_cndmask_b32_e64 v41, v41, v42, s[8:9]
	v_cndmask_b32_e64 v40, v40, v44, s[8:9]
	s_waitcnt lgkmcnt(1)
	v_add_f32_e32 v41, v41, v43
	ds_bpermute_b32 v42, v86, v41
	s_waitcnt lgkmcnt(1)
	v_add_f32_e32 v40, v40, v45
	ds_bpermute_b32 v43, v86, v40
	s_waitcnt lgkmcnt(1)
	v_add_f32_e32 v41, v41, v42
	ds_bpermute_b32 v42, v87, v41
	s_waitcnt lgkmcnt(1)
	v_add_f32_e32 v40, v40, v43
	ds_bpermute_b32 v43, v87, v40
	s_waitcnt lgkmcnt(1)
	v_add_f32_e32 v41, v41, v42
	ds_bpermute_b32 v42, v82, v41
	s_waitcnt lgkmcnt(1)
	v_add_f32_e32 v40, v40, v43
	ds_bpermute_b32 v43, v82, v40
	s_waitcnt lgkmcnt(1)
	v_max_f32_e32 v42, v42, v42
	v_max_f32_e32 v42, v41, v42
	s_waitcnt lgkmcnt(0)
	v_max_f32_e32 v43, v43, v43
	ds_bpermute_b32 v44, v83, v42
	v_max_f32_e32 v43, v40, v43
	ds_bpermute_b32 v45, v83, v43
	s_waitcnt lgkmcnt(1)
	v_max_f32_e32 v44, v44, v44
	v_max_f32_e32 v42, v42, v44
	s_waitcnt lgkmcnt(0)
	v_max_f32_e32 v44, v45, v45
	v_max_f32_e32 v43, v43, v44
	ds_bpermute_b32 v45, v84, v42
	ds_bpermute_b32 v44, v84, v43
	s_waitcnt lgkmcnt(1)
	v_max_f32_e32 v45, v45, v45
	s_waitcnt lgkmcnt(0)
	v_max_f32_e32 v44, v44, v44
	v_max_f32_e32 v42, v42, v45
	v_max_f32_e32 v43, v43, v44
	ds_bpermute_b32 v45, v85, v42
	ds_bpermute_b32 v44, v85, v43
	s_waitcnt lgkmcnt(1)
	v_max_f32_e32 v45, v45, v45
	s_waitcnt lgkmcnt(0)
	v_max_f32_e32 v44, v44, v44
	v_max_f32_e32 v42, v42, v45
	v_max_f32_e32 v43, v43, v44
	v_sub_f32_e32 v41, v41, v42
	v_sub_f32_e32 v40, v40, v43
	v_mul_f32_e32 v41, 0x3fb8aa3b, v41
	v_mul_f32_e32 v40, 0x3fb8aa3b, v40
	v_exp_f32_e32 v41, v41
	v_exp_f32_e32 v40, v40
	ds_bpermute_b32 v42, v82, v41
	ds_bpermute_b32 v43, v82, v40
	s_waitcnt lgkmcnt(1)
	v_add_f32_e32 v42, v41, v42
	s_waitcnt lgkmcnt(0)
	v_add_f32_e32 v43, v40, v43
	ds_bpermute_b32 v44, v83, v42
	ds_bpermute_b32 v45, v83, v43
	s_waitcnt lgkmcnt(1)
	v_add_f32_e32 v42, v42, v44
	s_waitcnt lgkmcnt(0)
	v_add_f32_e32 v44, v43, v45
	ds_bpermute_b32 v43, v84, v42
	ds_bpermute_b32 v45, v84, v44
	s_waitcnt lgkmcnt(1)
	v_add_f32_e32 v43, v42, v43
	s_waitcnt lgkmcnt(0)
	v_add_f32_e32 v42, v44, v45
	ds_bpermute_b32 v45, v85, v43
	ds_bpermute_b32 v44, v85, v42
	s_and_saveexec_b64 s[12:13], s[10:11]
	s_cbranch_execz .LBB0_801
	s_waitcnt lgkmcnt(1)
	v_add_f32_e32 v43, v43, v45
	v_div_scale_f32 v45, s[14:15], v43, v43, v41
	v_rcp_f32_e32 v46, v45
	s_waitcnt lgkmcnt(0)
	v_add_f32_e32 v44, v42, v44
	v_fma_f32 v42, -v45, v46, 1.0
	v_fmac_f32_e32 v46, v42, v46
	v_div_scale_f32 v42, vcc, v41, v43, v41
	v_mul_f32_e32 v47, v42, v46
	v_fma_f32 v48, -v45, v47, v42
	v_fmac_f32_e32 v47, v48, v46
	v_fma_f32 v42, -v45, v47, v42
	v_div_scale_f32 v45, s[14:15], v44, v44, v40
	v_div_fmas_f32 v42, v42, v46, v47
	v_rcp_f32_e32 v46, v45
	v_div_fixup_f32 v41, v42, v43, v41
	v_lshl_add_u64 v[42:43], s[18:19], 2, v[34:35]
	global_store_dword v[42:43], v41, off
	v_fma_f32 v41, -v45, v46, 1.0
	v_fmac_f32_e32 v46, v41, v46
	v_div_scale_f32 v41, vcc, v40, v44, v40
	v_mul_f32_e32 v42, v41, v46
	v_fma_f32 v43, -v45, v42, v41
	v_fmac_f32_e32 v42, v43, v46
	v_fma_f32 v41, -v45, v42, v41
	v_div_fmas_f32 v41, v41, v46, v42
	v_div_fixup_f32 v42, v41, v44, v40
	v_lshl_add_u64 v[40:41], s[16:17], 2, v[34:35]
	global_store_dword v[40:41], v42, off
	s_branch .LBB0_801
